# NSA top-k radix select: drop redundant re-ballot per bit
# speedup vs baseline: 1.0240x; 1.0113x over previous
.LBB0_316:
	s_lshl_b32 s1, 1, s0
	s_or_b32 s4, s1, s14
	s_sub_i32 s1, 0, s1
	v_and_b32_e32 v5, s1, v4
	v_cmp_eq_u32_e32 vcc, s4, v5
	s_and_b64 s[2:3], s[54:55], vcc
	v_and_b32_e32 v5, s1, v3
	s_bcnt1_i32_b64 s5, s[2:3]
	v_cmp_eq_u32_e32 vcc, s4, v5
	s_and_b64 s[2:3], s[52:53], vcc
	s_bcnt1_i32_b64 s1, s[2:3]
	s_add_i32 s1, s1, s5
	s_cmp_lt_i32 s1, s15
	s_cselect_b32 s1, s1, 0
	s_cselect_b32 s14, s14, s4
	s_sub_i32 s15, s15, s1
	s_add_i32 s0, s0, -1
	s_cmp_eq_u32 s0, -1
	s_cbranch_scc0 .LBB0_316
	v_cmp_eq_u32_e32 vcc, s14, v4
	v_cmp_eq_u32_e64 s[0:1], s14, v3
	s_and_b64 s[10:11], s[54:55], vcc
	v_cndmask_b32_e64 v5, 0, 1, s[10:11]
	s_and_b64 s[4:5], s[52:53], s[0:1]
	v_cmp_ne_u32_e32 vcc, 0, v5
	v_cndmask_b32_e64 v5, 0, 1, s[4:5]
	v_cmp_ne_u32_e64 s[0:1], 0, v5
	s_mov_b64 s[2:3], -1
	s_and_saveexec_b64 s[12:13], s[8:9]
	s_cbranch_execz .LBB0_319
	v_and_b32_e32 v6, vcc_lo, v118
	v_and_b32_e32 v5, vcc_hi, v115
	v_bcnt_u32_b32 v6, v6, 0
	v_bcnt_u32_b32 v5, v5, v6
	v_cmp_lt_u32_e64 s[2:3], s14, v4
	s_and_b64 s[16:17], s[54:55], s[2:3]
	v_cmp_gt_i32_e64 s[2:3], s15, v5
	s_and_b64 s[2:3], s[10:11], s[2:3]
	s_or_b64 s[2:3], s[16:17], s[2:3]
	s_orn2_b64 s[2:3], s[2:3], exec

.LBB0_322:
	s_lshl_b32 s0, 1, s2
	s_sub_i32 s4, 0, s0
	s_or_b32 s3, s0, s16
	v_and_b32_e32 v5, s4, v3
	v_cmp_eq_u32_e64 s[0:1], s3, v5
	s_and_b64 s[0:1], s[54:55], s[0:1]
	v_and_b32_e32 v5, s4, v4
	s_bcnt1_i32_b64 s5, s[0:1]
	v_cmp_eq_u32_e64 s[0:1], s3, v5
	s_and_b64 s[0:1], s[52:53], s[0:1]
	s_bcnt1_i32_b64 s0, s[0:1]
	s_add_i32 s0, s0, s5
	s_cmp_lt_i32 s0, s17
	s_cselect_b32 s0, s0, 0
	s_cselect_b32 s16, s16, s3
	s_sub_i32 s17, s17, s0
	s_add_i32 s2, s2, -1
	s_cmp_lg_u32 s2, -1
	s_cbranch_scc1 .LBB0_322
	v_cmp_eq_u32_e64 s[0:1], s16, v3
	v_cmp_eq_u32_e64 s[2:3], s16, v4
	s_and_b64 s[12:13], s[54:55], s[0:1]
	v_cndmask_b32_e64 v5, 0, 1, s[12:13]
	s_and_b64 s[10:11], s[52:53], s[2:3]
	v_cmp_ne_u32_e64 s[0:1], 0, v5
	v_cndmask_b32_e64 v5, 0, 1, s[10:11]
	v_cmp_ne_u32_e64 s[2:3], 0, v5
	s_mov_b64 s[4:5], -1
	s_and_saveexec_b64 s[14:15], s[8:9]
	s_cbranch_execz .LBB0_325
	v_and_b32_e32 v6, s0, v118
	v_and_b32_e32 v5, s1, v115
	v_bcnt_u32_b32 v6, v6, 0
	v_bcnt_u32_b32 v5, v5, v6
	v_cmp_lt_u32_e64 s[4:5], s16, v3
	s_and_b64 s[18:19], s[54:55], s[4:5]
	v_cmp_gt_i32_e64 s[4:5], s17, v5
	s_and_b64 s[4:5], s[12:13], s[4:5]
	s_or_b64 s[4:5], s[18:19], s[4:5]
	s_orn2_b64 s[4:5], s[4:5], exec

.LBB0_334:
	s_lshl_b32 s0, 1, s2
	s_sub_i32 s4, 0, s0
	s_or_b32 s3, s0, s16
	v_and_b32_e32 v1, s4, v3
	v_cmp_eq_u32_e64 s[0:1], s3, v1
	s_and_b64 s[0:1], s[54:55], s[0:1]
	v_and_b32_e32 v1, s4, v4
	s_bcnt1_i32_b64 s5, s[0:1]
	v_cmp_eq_u32_e64 s[0:1], s3, v1
	s_and_b64 s[0:1], s[52:53], s[0:1]
	s_bcnt1_i32_b64 s0, s[0:1]
	s_add_i32 s0, s0, s5
	s_cmp_lt_i32 s0, s17
	s_cselect_b32 s0, s0, 0
	s_cselect_b32 s16, s16, s3
	s_sub_i32 s17, s17, s0
	s_add_i32 s2, s2, -1
	s_cmp_lg_u32 s2, -1
	s_cbranch_scc1 .LBB0_334
	v_cmp_eq_u32_e64 s[0:1], s16, v3
	v_cmp_eq_u32_e64 s[2:3], s16, v4
	s_and_b64 s[12:13], s[54:55], s[0:1]
	v_cndmask_b32_e64 v1, 0, 1, s[12:13]
	s_and_b64 s[10:11], s[52:53], s[2:3]
	v_cmp_ne_u32_e64 s[0:1], 0, v1
	v_cndmask_b32_e64 v1, 0, 1, s[10:11]
	v_cmp_ne_u32_e64 s[2:3], 0, v1
	s_mov_b64 s[4:5], -1
	s_and_saveexec_b64 s[14:15], s[8:9]
	s_cbranch_execz .LBB0_337
	v_and_b32_e32 v2, s0, v118
	v_and_b32_e32 v1, s1, v115
	v_bcnt_u32_b32 v2, v2, 0
	v_bcnt_u32_b32 v1, v1, v2
	v_cmp_lt_u32_e64 s[4:5], s16, v3
	s_and_b64 s[8:9], s[54:55], s[4:5]
	v_cmp_gt_i32_e64 s[4:5], s17, v1
	s_and_b64 s[4:5], s[12:13], s[4:5]
	s_or_b64 s[4:5], s[8:9], s[4:5]
	s_orn2_b64 s[4:5], s[4:5], exec
